# grid barrier: the last XCD leader releases every XCC slot itself (16-lane atomic); other leaders no longer relay after polling TOP
# speedup vs baseline: 1.0108x; 1.0018x over previous
.LBB0_252:
	s_andn2_saveexec_b64 s[14:15], s[14:15]
	s_cbranch_execz .LBB0_272
	s_mov_b64 s[14:15], exec
	s_mov_b64 s[100:101], s[10:11]
	buffer_wbl2 sc1
	s_waitcnt lgkmcnt(0)
	s_waitcnt vmcnt(0)
	v_mbcnt_lo_u32_b32 v1, s14, 0
	v_mbcnt_hi_u32_b32 v1, s15, v1
	v_cmp_eq_u32_e32 vcc, 0, v1
	s_and_saveexec_b64 s[16:17], vcc
	s_cbranch_execz .LBB0_255
	s_bcnt1_i32_b64 s3, s[14:15]
	v_mov_b32_e32 v2, 0x3000
	v_mov_b32_e32 v3, s3
	global_atomic_add v2, v2, v3, s[10:11] offset:1024 sc0
.LBB0_255:
	s_or_b64 exec, exec, s[16:17]
	v_cvt_f32_u32_e32 v3, v0
	s_waitcnt vmcnt(0)
	v_readfirstlane_b32 s3, v2
	s_add_u32 s16, s10, 0x3400
	s_addc_u32 s17, s11, 0
	v_rcp_iflag_f32_e32 v3, v3
	v_add_u32_e32 v1, s3, v1
	v_add_u32_e32 v4, 1, v1
	s_mov_b64 s[18:19], 0
	v_mul_f32_e32 v2, 0x4f7ffffe, v3
	v_cvt_u32_f32_e32 v2, v2
	v_sub_u32_e32 v3, 0, v0
	v_mul_lo_u32 v3, v3, v2
	v_mul_hi_u32 v3, v2, v3
	v_add_u32_e32 v2, v2, v3
	v_mul_hi_u32 v2, v1, v2
	v_mul_lo_u32 v3, v2, v0
	v_sub_u32_e32 v1, v1, v3
	v_add_u32_e32 v5, 1, v2
	v_cmp_ge_u32_e32 vcc, v1, v0
	v_sub_u32_e32 v3, v1, v0
	s_nop 0
	v_cndmask_b32_e32 v2, v2, v5, vcc
	v_cndmask_b32_e32 v1, v1, v3, vcc
	v_add_u32_e32 v3, 1, v2
	v_cmp_ge_u32_e32 vcc, v1, v0
	s_nop 1
	v_cndmask_b32_e32 v2, v2, v3, vcc
	v_mul_lo_u32 v1, v0, v2
	v_add_u32_e32 v5, v1, v0
	v_cmp_ne_u32_e32 vcc, v4, v5
	v_mov_b64_e32 v[0:1], s[16:17]
	s_mov_b64 s[98:99], vcc
	s_and_saveexec_b64 s[14:15], vcc
	s_cbranch_execz .LBB0_267
	v_mov_b32_e32 v0, 0
	global_load_dword v1, v0, s[16:17] sc1
	s_mov_b64 s[22:23], 0
	s_waitcnt vmcnt(0)
	v_cmp_lt_u32_e32 vcc, v1, v5
	s_and_saveexec_b64 s[20:21], vcc
	s_cbranch_execz .LBB0_266
	s_add_u32 s18, s10, 0x200
	s_addc_u32 s19, s11, 0
	s_mov_b32 s3, 1
	s_mov_b64 s[10:11], 0
	s_branch .LBB0_259

.LBB0_269:
	s_or_b64 exec, exec, s[10:11]
	s_mov_b64 s[10:11], exec
	v_mbcnt_lo_u32_b32 v0, s10, 0
	v_mbcnt_hi_u32_b32 v0, s11, v0
	v_cmp_eq_u32_e32 vcc, 0, v0
	s_waitcnt vmcnt(0)
	s_and_saveexec_b64 s[14:15], vcc
	s_cbranch_execz .LBB0_271
	s_bcnt1_i32_b64 s3, s[10:11]
	s_and_b64 vcc, s[98:99], exec
	s_cbranch_vccnz .Lxb_norel_0
	s_mov_b64 s[98:99], exec
	s_mov_b64 exec, 0xffff
	v_mbcnt_lo_u32_b32 v0, -1, 0
	v_lshlrev_b32_e32 v0, 8, v0
	v_add_u32_e32 v0, 0x2400, v0
	v_mov_b32_e32 v1, 1
	global_atomic_add v0, v1, s[100:101]
	s_mov_b64 exec, s[98:99]
.Lxb_norel_0:
.LBB0_271:
	s_or_b64 exec, exec, s[14:15]
	s_waitcnt vmcnt(0)

.LBB0_528:
	s_andn2_saveexec_b64 s[10:11], s[10:11]
	s_cbranch_execz .LBB0_548
	s_mov_b64 s[10:11], exec
	s_mov_b64 s[100:101], s[6:7]
	buffer_wbl2 sc1
	s_waitcnt lgkmcnt(0)
	s_waitcnt vmcnt(0)
	v_mbcnt_lo_u32_b32 v1, s10, 0
	v_mbcnt_hi_u32_b32 v1, s11, v1
	v_cmp_eq_u32_e32 vcc, 0, v1
	s_and_saveexec_b64 s[12:13], vcc
	s_cbranch_execz .LBB0_531
	s_bcnt1_i32_b64 s3, s[10:11]
	v_mov_b32_e32 v2, 0x3000
	v_mov_b32_e32 v3, s3
	global_atomic_add v2, v2, v3, s[6:7] offset:1024 sc0
.LBB0_531:
	s_or_b64 exec, exec, s[12:13]
	v_cvt_f32_u32_e32 v3, v0
	s_waitcnt vmcnt(0)
	v_readfirstlane_b32 s3, v2
	s_add_u32 s12, s6, 0x3400
	s_addc_u32 s13, s7, 0
	v_rcp_iflag_f32_e32 v3, v3
	v_add_u32_e32 v1, s3, v1
	v_add_u32_e32 v4, 1, v1
	s_mov_b64 s[14:15], 0
	v_mul_f32_e32 v2, 0x4f7ffffe, v3
	v_cvt_u32_f32_e32 v2, v2
	v_sub_u32_e32 v3, 0, v0
	v_mul_lo_u32 v3, v3, v2
	v_mul_hi_u32 v3, v2, v3
	v_add_u32_e32 v2, v2, v3
	v_mul_hi_u32 v2, v1, v2
	v_mul_lo_u32 v3, v2, v0
	v_sub_u32_e32 v1, v1, v3
	v_add_u32_e32 v5, 1, v2
	v_cmp_ge_u32_e32 vcc, v1, v0
	v_sub_u32_e32 v3, v1, v0
	s_nop 0
	v_cndmask_b32_e32 v2, v2, v5, vcc
	v_cndmask_b32_e32 v1, v1, v3, vcc
	v_add_u32_e32 v3, 1, v2
	v_cmp_ge_u32_e32 vcc, v1, v0
	s_nop 1
	v_cndmask_b32_e32 v2, v2, v3, vcc
	v_mul_lo_u32 v1, v0, v2
	v_add_u32_e32 v5, v1, v0
	v_cmp_ne_u32_e32 vcc, v4, v5
	v_mov_b64_e32 v[0:1], s[12:13]
	s_mov_b64 s[98:99], vcc
	s_and_saveexec_b64 s[10:11], vcc
	s_cbranch_execz .LBB0_543
	v_mov_b32_e32 v0, 0
	global_load_dword v1, v0, s[12:13] sc1
	s_mov_b64 s[18:19], 0
	s_waitcnt vmcnt(0)
	v_cmp_lt_u32_e32 vcc, v1, v5
	s_and_saveexec_b64 s[16:17], vcc
	s_cbranch_execz .LBB0_542
	s_add_u32 s14, s6, 0x200
	s_addc_u32 s15, s7, 0
	s_mov_b32 s3, 1
	s_mov_b64 s[6:7], 0
	s_branch .LBB0_535

.LBB0_545:
	s_or_b64 exec, exec, s[6:7]
	s_mov_b64 s[6:7], exec
	v_mbcnt_lo_u32_b32 v0, s6, 0
	v_mbcnt_hi_u32_b32 v0, s7, v0
	v_cmp_eq_u32_e32 vcc, 0, v0
	s_waitcnt vmcnt(0)
	s_and_saveexec_b64 s[10:11], vcc
	s_cbranch_execz .LBB0_547
	s_bcnt1_i32_b64 s3, s[6:7]
	s_and_b64 vcc, s[98:99], exec
	s_cbranch_vccnz .Lxb_norel_2
	s_mov_b64 s[98:99], exec
	s_mov_b64 exec, 0xffff
	v_mbcnt_lo_u32_b32 v0, -1, 0
	v_lshlrev_b32_e32 v0, 8, v0
	v_add_u32_e32 v0, 0x2400, v0
	v_mov_b32_e32 v1, 1
	global_atomic_add v0, v1, s[100:101]
	s_mov_b64 exec, s[98:99]
.Lxb_norel_2:
.LBB0_547:
	s_or_b64 exec, exec, s[10:11]
	s_waitcnt vmcnt(0)
